# fk_compute inner loop software-pipelined (next tile's H2 loads prefetched one iteration ahead) + in-proj rotation
# baseline (speedup 1.0000x reference)
; __device__ __forceinline__ void fk_compute(const Args& a, int j, int gw, int NGW, int lane) {
;     ...
;     for (int it = gw; it < 2048; it += NGW) {
;         const int pq = it & 3, cht = (it >> 2) & 63, dir = (it >> 8) & 1, o = (it >> 9) & 1, set = it >> 10;
;         const int L = set ? L_S : L_P, offs = set ? FK_OFFS_S : FK_OFFS_P, len = set ? FK_LEN_S : FK_LEN_P, nbase = set ? L_P : 0;
;         bf16_t* base = FK + (set ? FK_SAMPLE_OFF : 0);
;         const int ch = cht * 16 + n16;
;         bf16x8 Bh0, Bl0, Bh1, Bl1;
;         {
;             const float* wp = w3 + (o * 2 + dir) * 1024 + ch;
;             f32x4 w0, w1, w2, w3v;
; #pragma unroll
;             for (int i = 0; i < 4; ++i) { w0[i] = wp[(size_t)(8 * g + i) * 4096]; w1[i] = wp[(size_t)(8 * g + 4 + i) * 4096];
;                 w2[i] = wp[(size_t)(32 + 8 * g + i) * 4096]; w3v[i] = wp[(size_t)(36 + 8 * g + i) * 4096]; }
;             split8(w0, w1, Bh0, Bl0); split8(w2, w3v, Bh1, Bl1);
;         }
;         const float mind = -3.0701134573253944f, maxd = -15.350567286626972f;
;         const float delta = fabsf(mind + (maxd - mind) * ((float)ch * (1.0f / 1023.0f)));
;         const float skipv = skip[o * 1024 + ch];
;         const float tinv = 1.0f / (float)(L - 1);
;         bf16_t* rowp = base + ((size_t)o * 1024 + ch) * len;
;         const int tq = offs / 64;
; #pragma unroll 2
;         for (int tile = pq * tq; tile < (pq + 1) * tq; ++tile) {
;             const int n0 = tile * 16 + dir;
;             const int nr = n0 + n16, nrc = nr < L ? nr : L - 1;
;             const float* hp = H2 + (size_t)(nbase + nrc) * 64 + 8 * g;
;             const f32x4 h0 = *(const f32x4*)hp, h1 = *(const f32x4*)(hp + 4), h2 = *(const f32x4*)(hp + 32), h3 = *(const f32x4*)(hp + 36);
.LBB0_986:
	s_waitcnt vmcnt(0)
	s_add_i32 s14, s14, s15
	s_cmpk_gt_i32 s14, 0x7ff
	s_cbranch_scc1 .LBB0_993
.LBB0_987:
	s_bitcmp1_b32 s14, 8
	s_cselect_b64 s[10:11], -1, 0
	s_lshl_b32 s2, s14, 2
	s_bfe_u32 s21, s14, 0x10008
	s_bfe_u32 s13, s14, 0x10009
	s_and_b32 s2, s2, 0x3f0
	s_cmpk_lt_u32 s14, 0x400
	s_movk_i32 s3, 0x2010
	s_cselect_b32 s22, s3, 0x1010
	v_or_b32_e32 v34, s2, v30
	s_movk_i32 s2, 0x2200
	s_movk_i32 s3, 0x4400
	s_cselect_b32 s2, s2, 0x1200
	s_cselect_b32 s23, 0, 0x2010
	s_cselect_b32 s30, s3, 0x2400
	s_cselect_b32 s3, 0, 0x4400000
	s_lshl_b32 s25, s14, 4
	s_and_b32 s25, s25, 0x1000
	s_lshl_b32 s28, s13, 13
	s_add_i32 s24, s22, -1
	s_lshr_b32 s12, s2, 6
	s_or_b32 s25, s28, s25
	s_add_u32 s28, s16, s25
	s_addc_u32 s29, s17, 0
	v_lshlrev_b32_e32 v32, 2, v34
	v_lshl_add_u64 v[0:1], s[28:29], 0, v[32:33]
	v_mov_b32_e32 v21, v33
	v_lshl_add_u64 v[0:1], v[0:1], 0, v[20:21]
	s_mov_b32 s25, 0x90000
	v_add_co_u32_e32 v2, vcc, s25, v0
	s_mov_b32 s25, 0x94000
	s_nop 0
	v_addc_co_u32_e32 v3, vcc, 0, v1, vcc
	v_add_co_u32_e32 v4, vcc, s25, v0
	s_mov_b32 s25, 0x98000
	s_nop 0
	v_addc_co_u32_e32 v5, vcc, 0, v1, vcc
	v_add_co_u32_e32 v6, vcc, s25, v0
	s_mov_b32 s25, 0x9c000
	s_nop 0
	v_addc_co_u32_e32 v7, vcc, 0, v1, vcc
	v_add_co_u32_e32 v8, vcc, s25, v0
	s_mov_b32 s25, 0x80000
	s_nop 0
	v_addc_co_u32_e32 v9, vcc, 0, v1, vcc
	v_add_co_u32_e32 v10, vcc, s25, v0
	s_mov_b32 s25, 0x84000
	s_nop 0
	v_addc_co_u32_e32 v11, vcc, 0, v1, vcc
	v_add_co_u32_e32 v12, vcc, s25, v0
	s_mov_b32 s25, 0x88000
	s_nop 0
	v_addc_co_u32_e32 v13, vcc, 0, v1, vcc
	global_load_dword v10, v[10:11], off
	s_nop 0
	global_load_dword v11, v[12:13], off
	v_add_co_u32_e32 v12, vcc, s25, v0
	s_mov_b32 s25, 0x8c000
	s_nop 0
	v_addc_co_u32_e32 v13, vcc, 0, v1, vcc
	v_add_co_u32_e32 v14, vcc, s25, v0
	s_mov_b32 s25, 0x10000
	s_nop 0
	v_addc_co_u32_e32 v15, vcc, 0, v1, vcc
	v_add_co_u32_e32 v22, vcc, s25, v0
	global_load_dword v15, v[14:15], off
	s_nop 0
	v_addc_co_u32_e32 v23, vcc, 0, v1, vcc
	s_mov_b32 s25, 0x14000
	v_add_co_u32_e32 v24, vcc, s25, v0
	s_movk_i32 s25, 0x4000
	s_nop 0
	v_addc_co_u32_e32 v25, vcc, 0, v1, vcc
	global_load_dword v26, v[2:3], off
	global_load_dword v27, v[4:5], off
	global_load_dword v14, v[12:13], off
	s_nop 0
	global_load_dword v12, v[6:7], off
	global_load_dword v13, v[8:9], off
	global_load_dword v28, v[0:1], off
	v_add_co_u32_e32 v2, vcc, s25, v0
	s_mov_b32 s25, 0x8000
	s_nop 0
	v_addc_co_u32_e32 v3, vcc, 0, v1, vcc
	global_load_dword v29, v[2:3], off
	v_add_co_u32_e32 v2, vcc, s25, v0
	s_mov_b32 s25, 0xc000
	s_nop 0
	v_addc_co_u32_e32 v3, vcc, 0, v1, vcc
	v_add_co_u32_e32 v4, vcc, s25, v0
	s_mov_b32 s25, 0x18000
	s_nop 0
	v_addc_co_u32_e32 v5, vcc, 0, v1, vcc
	global_load_dword v22, v[22:23], off
	s_nop 0
	global_load_dword v23, v[24:25], off
	s_nop 0
	global_load_dword v24, v[2:3], off
	global_load_dword v25, v[4:5], off
	v_add_co_u32_e32 v2, vcc, s25, v0
	s_mov_b32 s25, 0x1c000
	s_nop 0
	v_addc_co_u32_e32 v3, vcc, 0, v1, vcc
	v_add_co_u32_e32 v0, vcc, s25, v0
	v_mov_b32_e32 v5, 0xc0447cbd
	s_nop 0
	v_addc_co_u32_e32 v1, vcc, 0, v1, vcc
	global_load_dword v36, v[2:3], off
	global_load_dword v37, v[0:1], off
	v_lshl_or_b32 v0, s13, 10, v34
	v_lshlrev_b32_e32 v1, 2, v0
	global_load_dword v21, v1, s[4:5]
	v_cvt_f32_u32_e32 v1, s24
	v_cvt_f32_u32_e32 v2, v34
	v_mul_u32_u24_e32 v32, s30, v0
	s_lshl_b32 s2, s2, 1
	v_div_scale_f32 v3, s[28:29], v1, v1, 1.0
	v_rcp_f32_e32 v4, v3
	v_mul_f32_e32 v2, 0xba802008, v2
	v_fmamk_f32 v34, v2, 0x41447cbd, v5
	s_or_b32 s56, s2, s3
	v_fma_f32 v2, -v3, v4, 1.0
	v_fmac_f32_e32 v4, v2, v4
	v_div_scale_f32 v2, vcc, 1.0, v1, 1.0
	v_mul_f32_e32 v5, v2, v4
	v_fma_f32 v6, -v3, v5, v2
	v_fmac_f32_e32 v5, v6, v4
	v_fma_f32 v2, -v3, v5, v2
	v_div_fmas_f32 v2, v2, v4, v5
	v_div_fixup_f32 v35, v2, v1, 1.0
	s_mul_i32 s2, s20, s12
	v_lshlrev_b32_e32 v32, 1, v32
	s_or_b32 s3, s2, s21
	s_mul_i32 s25, s12, s19
	s_mul_i32 s28, s12, s18
	s_waitcnt vmcnt(0)
	v_cvt_pk_bf16_f32 v0, v10, v11
	v_lshlrev_b32_e32 v2, 16, v0
	v_and_b32_e32 v3, 0xffff0000, v0
	v_pk_add_f32 v[2:3], v[10:11], v[2:3] neg_lo:[0,1] neg_hi:[0,1]
	s_waitcnt vmcnt(11)
	v_cvt_pk_bf16_f32 v1, v14, v15
	v_cvt_pk_bf16_f32 v4, v2, v3
	v_lshlrev_b32_e32 v2, 16, v1
	v_and_b32_e32 v3, 0xffff0000, v1
	v_pk_add_f32 v[2:3], v[14:15], v[2:3] neg_lo:[0,1] neg_hi:[0,1]
	s_nop 0
	v_cvt_pk_bf16_f32 v5, v2, v3
	v_cvt_pk_bf16_f32 v2, v26, v27
	s_waitcnt vmcnt(9)
	v_cvt_pk_bf16_f32 v3, v12, v13
	v_lshlrev_b32_e32 v6, 16, v2
	v_and_b32_e32 v7, 0xffff0000, v2
	v_lshlrev_b32_e32 v8, 16, v3
	v_and_b32_e32 v9, 0xffff0000, v3
	v_pk_add_f32 v[6:7], v[26:27], v[6:7] neg_lo:[0,1] neg_hi:[0,1]
	v_pk_add_f32 v[8:9], v[12:13], v[8:9] neg_lo:[0,1] neg_hi:[0,1]
	v_cvt_pk_bf16_f32 v6, v6, v7
	v_cvt_pk_bf16_f32 v7, v8, v9
	s_waitcnt vmcnt(7)
	v_cvt_pk_bf16_f32 v8, v28, v29
	v_lshlrev_b32_e32 v10, 16, v8
	v_and_b32_e32 v11, 0xffff0000, v8
	v_pk_add_f32 v[10:11], v[28:29], v[10:11] neg_lo:[0,1] neg_hi:[0,1]
	s_waitcnt vmcnt(3)
	v_cvt_pk_bf16_f32 v9, v24, v25
	v_cvt_pk_bf16_f32 v12, v10, v11
	v_lshlrev_b32_e32 v10, 16, v9
	v_and_b32_e32 v11, 0xffff0000, v9
	v_pk_add_f32 v[10:11], v[24:25], v[10:11] neg_lo:[0,1] neg_hi:[0,1]
	v_lshl_add_u64 v[24:25], s[56:57], 0, v[32:33]
	v_cvt_pk_bf16_f32 v13, v10, v11
	v_cvt_pk_bf16_f32 v10, v22, v23
	v_lshlrev_b32_e32 v14, 16, v10
	v_and_b32_e32 v15, 0xffff0000, v10
	s_waitcnt vmcnt(1)
	v_cvt_pk_bf16_f32 v11, v36, v37
	v_pk_add_f32 v[14:15], v[22:23], v[14:15] neg_lo:[0,1] neg_hi:[0,1]
	v_lshlrev_b32_e32 v22, 16, v11
	v_and_b32_e32 v23, 0xffff0000, v11
	v_pk_add_f32 v[22:23], v[36:37], v[22:23] neg_lo:[0,1] neg_hi:[0,1]
	v_add_u32_e32 v36, s2, v31
	s_lshl_b32 s56, s3, 1
	v_add_lshl_u32 v26, v36, s21, 1
	v_cvt_pk_bf16_f32 v14, v14, v15
	v_cvt_pk_bf16_f32 v15, v22, v23
	v_lshl_add_u64 v[22:23], v[24:25], 0, s[56:57]
	v_sub_co_u32_e32 v24, vcc, v24, v26
	v_lshl_add_u64 v[22:23], v[18:19], 0, v[22:23]
	s_nop 0
	v_subbrev_co_u32_e32 v25, vcc, 0, v25, vcc
	v_lshl_add_u64 v[24:25], s[8:9], 0, v[24:25]
	v_add_u32_e32 v37, s2, v30
	v_mov_b32_e32 v103, 0
	v_add_u32_e32 v102, s21, v37
	v_min_u32_e32 v102, s24, v102
	v_add_lshl_u32 v102, v102, s23, 8
	v_lshl_add_u64 v[100:101], v[16:17], 0, v[102:103]
	global_load_dwordx4 v[84:87], v[100:101], off
	global_load_dwordx4 v[88:91], v[100:101], off offset:16
	global_load_dwordx4 v[92:95], v[100:101], off offset:128
	global_load_dwordx4 v[96:99], v[100:101], off offset:144
	s_waitcnt vmcnt(0)
	s_branch .LBB0_989

; __device__ __forceinline__ unsigned cvtpk(float lo, float hi) { f32x2 v = {lo, hi}; bf16x2_t b = __builtin_convertvector(v, bf16x2_t); return __builtin_bit_cast(unsigned, b); }
; __device__ __forceinline__ void fk_compute(const Args& a, int j, int gw, int NGW, int lane) {
;     ...
;         for (int tile = pq * tq; tile < (pq + 1) * tq; ++tile) {
;             const int n0 = tile * 16 + dir;
;             const int nr = n0 + n16, nrc = nr < L ? nr : L - 1;
;             const float* hp = H2 + (size_t)(nbase + nrc) * 64 + 8 * g;
;             const f32x4 h0 = *(const f32x4*)hp, h1 = *(const f32x4*)(hp + 4), h2 = *(const f32x4*)(hp + 32), h3 = *(const f32x4*)(hp + 36);
;             bf16x8 Ah0, Al0, Ah1, Al1; split8(h0, h1, Ah0, Al0); split8(h2, h3, Ah1, Al1);
;             f32x4 acc = (f32x4){0.f, 0.f, 0.f, 0.f};
;             acc = __builtin_amdgcn_mfma_f32_16x16x32_bf16(Al0, Bh0, acc, 0, 0, 0);
;             acc = __builtin_amdgcn_mfma_f32_16x16x32_bf16(Al1, Bh1, acc, 0, 0, 0);
;             acc = __builtin_amdgcn_mfma_f32_16x16x32_bf16(Ah0, Bl0, acc, 0, 0, 0);
;             acc = __builtin_amdgcn_mfma_f32_16x16x32_bf16(Ah1, Bl1, acc, 0, 0, 0);
;             acc = __builtin_amdgcn_mfma_f32_16x16x32_bf16(Ah0, Bh0, acc, 0, 0, 0);
;             acc = __builtin_amdgcn_mfma_f32_16x16x32_bf16(Ah1, Bh1, acc, 0, 0, 0);
;             float v[4];
; #pragma unroll
;             for (int ii = 0; ii < 4; ++ii) {
;                 const int n = n0 + 4 * g + ii;
;                 float x = acc[ii] * __expf(-((float)n * tinv) * delta);
;                 if (dir == 0 && n == 0) x += skipv;
;                 v[ii] = n < L ? x : 0.f;
;             }
;             u32x2 pk;
;             if (dir == 0) { pk.x = cvtpk(v[0], v[1]); pk.y = cvtpk(v[2], v[3]); *(u32x2*)(rowp + offs + n0 + 4 * g) = pk; }
;             else { pk.x = cvtpk(v[3], v[2]); pk.y = cvtpk(v[1], v[0]); *(u32x2*)(rowp + offs - (n0 + 4 * g + 3)) = pk; }
.LBB0_989:
	s_waitcnt vmcnt(1)
	v_mov_b64_e32 v[26:27], v[84:85]
	v_mov_b64_e32 v[28:29], v[86:87]
	v_mov_b64_e32 v[38:39], v[88:89]
	v_mov_b64_e32 v[40:41], v[90:91]
	v_mov_b64_e32 v[42:43], v[92:93]
	v_mov_b64_e32 v[44:45], v[94:95]
	v_mov_b64_e32 v[46:47], v[96:97]
	v_mov_b64_e32 v[48:49], v[98:99]
	v_add_u32_e32 v102, s21, v37
	v_add_u32_e32 v102, 16, v102
	v_min_u32_e32 v102, s24, v102
	v_add_lshl_u32 v102, v102, s23, 8
	v_lshl_add_u64 v[100:101], v[16:17], 0, v[102:103]
	global_load_dwordx4 v[84:87], v[100:101], off
	global_load_dwordx4 v[88:91], v[100:101], off offset:16
	global_load_dwordx4 v[92:95], v[100:101], off offset:128
	global_load_dwordx4 v[96:99], v[100:101], off offset:144
	v_add_u32_e32 v32, s21, v36
	v_cvt_f32_u32_e32 v50, v32
	v_add_u32_e32 v74, 1, v32
	v_add_u32_e32 v75, 2, v32
	v_cvt_f32_i32_e32 v77, v74
	v_mul_f32_e64 v80, v35, -v50
	v_add_u32_e32 v76, 3, v32
	v_cvt_f32_i32_e32 v78, v75
	v_cvt_f32_i32_e32 v79, v76
	v_cmp_eq_u32_e64 s[2:3], 0, v32
	s_mov_b64 s[12:13], -1
	s_and_b64 vcc, exec, s[10:11]
	v_cvt_pk_bf16_f32 v50, v26, v27
	v_cvt_pk_bf16_f32 v51, v28, v29
	v_cvt_pk_bf16_f32 v52, v38, v39
	v_cvt_pk_bf16_f32 v53, v40, v41
	v_lshlrev_b32_e32 v58, 16, v50
	v_and_b32_e32 v59, 0xffff0000, v50
	v_lshlrev_b32_e32 v60, 16, v51
	v_and_b32_e32 v61, 0xffff0000, v51
	v_lshlrev_b32_e32 v62, 16, v52
	v_and_b32_e32 v63, 0xffff0000, v52
	v_lshlrev_b32_e32 v64, 16, v53
	v_and_b32_e32 v65, 0xffff0000, v53
	v_pk_add_f32 v[26:27], v[26:27], v[58:59] neg_lo:[0,1] neg_hi:[0,1]
	v_pk_add_f32 v[28:29], v[28:29], v[60:61] neg_lo:[0,1] neg_hi:[0,1]
	v_pk_add_f32 v[38:39], v[38:39], v[62:63] neg_lo:[0,1] neg_hi:[0,1]
	v_pk_add_f32 v[40:41], v[40:41], v[64:65] neg_lo:[0,1] neg_hi:[0,1]
	v_cvt_pk_bf16_f32 v26, v26, v27
	v_cvt_pk_bf16_f32 v27, v28, v29
	v_cvt_pk_bf16_f32 v28, v38, v39
	v_cvt_pk_bf16_f32 v29, v40, v41
	v_cvt_pk_bf16_f32 v54, v42, v43
	v_cvt_pk_bf16_f32 v55, v44, v45
	v_cvt_pk_bf16_f32 v56, v46, v47
	v_cvt_pk_bf16_f32 v57, v48, v49
	v_lshlrev_b32_e32 v66, 16, v54
	v_and_b32_e32 v67, 0xffff0000, v54
	v_lshlrev_b32_e32 v68, 16, v55
	v_and_b32_e32 v69, 0xffff0000, v55
	v_lshlrev_b32_e32 v70, 16, v56
	v_and_b32_e32 v71, 0xffff0000, v56
	v_lshlrev_b32_e32 v72, 16, v57
	v_and_b32_e32 v73, 0xffff0000, v57
	v_pk_add_f32 v[42:43], v[42:43], v[66:67] neg_lo:[0,1] neg_hi:[0,1]
	v_pk_add_f32 v[44:45], v[44:45], v[68:69] neg_lo:[0,1] neg_hi:[0,1]
	v_pk_add_f32 v[46:47], v[46:47], v[70:71] neg_lo:[0,1] neg_hi:[0,1]
	v_pk_add_f32 v[48:49], v[48:49], v[72:73] neg_lo:[0,1] neg_hi:[0,1]
	v_cvt_pk_bf16_f32 v38, v42, v43
	v_cvt_pk_bf16_f32 v39, v44, v45
	v_cvt_pk_bf16_f32 v40, v46, v47
	v_cvt_pk_bf16_f32 v41, v48, v49
	v_mfma_f32_16x16x32_bf16 v[26:29], v[26:29], v[8:11], 0
	v_mul_f32_e64 v42, |v34|, v80
	v_mul_f32_e64 v43, v35, -v77
	v_mul_f32_e64 v44, v35, -v78
	v_mfma_f32_16x16x32_bf16 v[26:29], v[38:41], v[0:3], v[26:29]
	v_mul_f32_e32 v39, 0x3fb8aa3b, v42
	v_mul_f32_e64 v40, |v34|, v43
	v_mul_f32_e64 v38, v35, -v79
	v_mfma_f32_16x16x32_bf16 v[26:29], v[50:53], v[12:15], v[26:29]
	v_mul_f32_e64 v41, |v34|, v44
	v_exp_f32_e32 v39, v39
	v_mul_f32_e32 v40, 0x3fb8aa3b, v40
	v_mfma_f32_16x16x32_bf16 v[26:29], v[54:57], v[4:7], v[26:29]
	v_mul_f32_e64 v38, |v34|, v38
	v_mul_f32_e32 v41, 0x3fb8aa3b, v41
	v_exp_f32_e32 v40, v40
	v_mfma_f32_16x16x32_bf16 v[26:29], v[50:53], v[8:11], v[26:29]
	v_mul_f32_e32 v38, 0x3fb8aa3b, v38
	v_exp_f32_e32 v41, v41
	v_exp_f32_e32 v38, v38
	v_mfma_f32_16x16x32_bf16 v[26:29], v[54:57], v[0:3], v[26:29]
	s_nop 7
	v_mul_f32_e32 v42, v39, v26
	v_fma_f32 v26, v39, v26, v21
	v_mul_f32_e32 v27, v40, v27
	v_cndmask_b32_e64 v26, v42, v26, s[2:3]
	v_cmp_gt_u32_e64 s[2:3], s22, v74
	v_mul_f32_e32 v28, v41, v28
	v_mul_f32_e32 v29, v38, v29
	v_cndmask_b32_e64 v27, 0, v27, s[2:3]
	v_cmp_gt_u32_e64 s[2:3], s22, v75
	s_nop 1
	v_cndmask_b32_e64 v28, 0, v28, s[2:3]
	v_cmp_gt_u32_e64 s[2:3], s22, v76
	s_nop 1
	v_cndmask_b32_e64 v29, 0, v29, s[2:3]
	v_cmp_gt_u32_e64 s[2:3], s22, v32
	s_nop 1
	v_cndmask_b32_e64 v26, 0, v26, s[2:3]
	s_cbranch_vccz .LBB0_991
	v_pk_mov_b32 v[38:39], v[28:29], v[28:29] op_sel:[1,0]
	v_pk_mov_b32 v[40:41], v[26:27], v[26:27] op_sel:[1,0]
	v_cvt_pk_bf16_f32 v38, v38, v39
	v_cvt_pk_bf16_f32 v39, v40, v41
	global_store_dwordx2 v[24:25], v[38:39], off
	s_mov_b64 s[12:13], 0
